# cmlp part 2 software-pipelined over the eight 16-column steps; LN stats once per workgroup; split 2/4 0/4
# baseline (speedup 1.0000x reference)
.Lcma_pf0:
	global_load_dwordx4 v[100:103], v200, s[46:47]
	global_load_dwordx4 v[116:119], v204, s[48:49]
	global_load_dwordx4 v[104:107], v201, s[46:47]
	global_load_dwordx4 v[120:123], v205, s[48:49]
	global_load_dwordx4 v[108:111], v202, s[46:47]
	global_load_dwordx4 v[124:127], v206, s[48:49]
	global_load_dwordx4 v[112:115], v203, s[46:47]
	global_load_dwordx4 v[128:131], v207, s[48:49]
	global_load_dwordx4 v[164:167], v209, s[14:15]
	global_load_dwordx4 v[168:171], v209, s[16:17]
	global_load_dwordx4 v[172:175], v209, s[16:17] offset:16
	global_load_dwordx4 v[176:179], v209, s[14:15] offset:16
	global_load_dword v236, v210, s[10:11]
	global_load_dwordx2 v[220:221], v211, s[6:7]
	global_load_dwordx2 v[222:223], v211, s[6:7] offset:32
	global_load_dwordx2 v[224:225], v211, s[6:7] offset:64
	global_load_dwordx2 v[226:227], v211, s[6:7] offset:96
	global_load_dwordx2 v[228:229], v211, s[6:7] offset:128
	global_load_dwordx2 v[230:231], v211, s[6:7] offset:160
	global_load_dwordx2 v[232:233], v211, s[6:7] offset:192
	global_load_dwordx2 v[234:235], v211, s[6:7] offset:224
	s_waitcnt vmcnt(0)
	v_readfirstlane_b32 s0, v195
	s_nop 1
	s_cmp_lt_u32 s0, 0x80
	s_cbranch_scc0 .Lcma_nostat
	v_pk_add_f32 v[56:57], v[132:133], v[134:135]
	v_pk_add_f32 v[60:61], v[136:137], v[138:139]
	v_pk_add_f32 v[56:57], v[56:57], 0 op_sel_hi:[1,0]
	v_pk_add_f32 v[58:59], v[140:141], v[142:143]
	v_pk_add_f32 v[56:57], v[56:57], v[60:61]
	v_pk_add_f32 v[60:61], v[144:145], v[146:147]
	v_pk_add_f32 v[56:57], v[56:57], v[58:59]
	v_pk_add_f32 v[58:59], v[148:149], v[150:151]
	v_pk_add_f32 v[56:57], v[56:57], v[60:61]
	v_pk_add_f32 v[60:61], v[152:153], v[154:155]
	v_pk_add_f32 v[56:57], v[56:57], v[58:59]
	v_pk_add_f32 v[58:59], v[156:157], v[158:159]
	v_pk_add_f32 v[56:57], v[56:57], v[60:61]
	v_pk_add_f32 v[60:61], v[160:161], v[162:163]
	v_pk_add_f32 v[56:57], v[56:57], v[58:59]
	s_nop 0
	v_pk_add_f32 v[56:57], v[56:57], v[60:61]
	s_nop 0
	v_pk_mul_f32 v[56:57], v[56:57], s[4:5] op_sel_hi:[1,0]
	s_nop 0
	v_fma_f32 v58, -v56, v56, v57
	v_max_f32_e32 v58, 0, v58
	v_add_f32_e32 v58, 0x358637bd, v58
	v_rsq_f32_e32 v57, v58
	s_nop 1
	ds_write_b64 v215, v[56:57]
.Lcma_nostat:
	s_branch .Lcma_copy
.Lcma_top:
	s_waitcnt vmcnt(8)
.Lcma_copy:
	s_mov_b64 s[12:13], s[6:7]
	v_mov_b32_e32 v0, v100
	v_mov_b32_e32 v1, v101
	v_mov_b32_e32 v2, v102
	v_mov_b32_e32 v3, v103
	v_mov_b32_e32 v4, v104
	v_mov_b32_e32 v5, v105
	v_mov_b32_e32 v6, v106
	v_mov_b32_e32 v7, v107
	v_mov_b32_e32 v8, v108
	v_mov_b32_e32 v9, v109
	v_mov_b32_e32 v10, v110
	v_mov_b32_e32 v11, v111
	v_mov_b32_e32 v12, v112
	v_mov_b32_e32 v13, v113
	v_mov_b32_e32 v14, v114
	v_mov_b32_e32 v15, v115
	v_mov_b32_e32 v16, v116
	v_mov_b32_e32 v17, v117
	v_mov_b32_e32 v18, v118
	v_mov_b32_e32 v19, v119
	v_mov_b32_e32 v20, v120
	v_mov_b32_e32 v21, v121
	v_mov_b32_e32 v22, v122
	v_mov_b32_e32 v23, v123
	v_mov_b32_e32 v24, v124
	v_mov_b32_e32 v25, v125
	v_mov_b32_e32 v26, v126
	v_mov_b32_e32 v27, v127
	v_mov_b32_e32 v28, v128
	v_mov_b32_e32 v29, v129
	v_mov_b32_e32 v30, v130
	v_mov_b32_e32 v31, v131
	v_mov_b32_e32 v38, v164
	v_mov_b32_e32 v39, v165
	v_mov_b32_e32 v40, v166
	v_mov_b32_e32 v41, v167
	v_mov_b32_e32 v42, v168
	v_mov_b32_e32 v43, v169
	v_mov_b32_e32 v44, v170
	v_mov_b32_e32 v45, v171
	v_mov_b32_e32 v46, v172
	v_mov_b32_e32 v47, v173
	v_mov_b32_e32 v48, v174
	v_mov_b32_e32 v49, v175
	v_mov_b32_e32 v50, v176
	v_mov_b32_e32 v51, v177
	v_mov_b32_e32 v52, v178
	v_mov_b32_e32 v53, v179
	v_mov_b32_e32 v70, v220
	v_mov_b32_e32 v71, v221
	v_mov_b32_e32 v72, v222
	v_mov_b32_e32 v73, v223
	v_mov_b32_e32 v74, v224
	v_mov_b32_e32 v75, v225
	v_mov_b32_e32 v76, v226
	v_mov_b32_e32 v77, v227
	v_mov_b32_e32 v78, v228
	v_mov_b32_e32 v79, v229
	v_mov_b32_e32 v80, v230
	v_mov_b32_e32 v81, v231
	v_mov_b32_e32 v82, v232
	v_mov_b32_e32 v83, v233
	v_mov_b32_e32 v84, v234
	v_mov_b32_e32 v85, v235
	v_mov_b32_e32 v86, v236
	s_cmp_gt_u32 s3, 1
	s_cbranch_scc0 .Lcma_nopf
	s_add_i32 s0, s5, 1
	s_and_b32 s1, s0, 7
	s_lshr_b32 s0, s0, 3
	s_lshl_b32 s0, s0, 7
	s_lshl_b32 s10, s1, 8
	s_lshl_b32 s11, s0, 11
	s_add_u32 s11, s11, s10
	s_add_u32 s46, s42, s11
	s_addc_u32 s47, s43, 0
	s_add_u32 s6, s96, s11
	s_addc_u32 s7, s97, 0
	s_lshl_b32 s10, s1, 15
	s_add_u32 s48, s8, s10
	s_addc_u32 s49, s9, 0
	s_lshl_b32 s10, s0, 7
	s_add_u32 s50, s44, s10
	s_addc_u32 s51, s45, 0
	s_lshl_b32 s10, s1, 9
	s_add_u32 s14, s36, s10
	s_addc_u32 s15, s37, 0
	s_add_u32 s16, s38, s10
	s_addc_u32 s17, s39, 0
	s_add_u32 s10, s40, s10
	s_addc_u32 s11, s41, 0
	global_load_dwordx4 v[100:103], v200, s[46:47]
	global_load_dwordx4 v[116:119], v204, s[48:49]
	global_load_dwordx4 v[104:107], v201, s[46:47]
	global_load_dwordx4 v[120:123], v205, s[48:49]
	global_load_dwordx4 v[108:111], v202, s[46:47]
	global_load_dwordx4 v[124:127], v206, s[48:49]
	global_load_dwordx4 v[112:115], v203, s[46:47]
	global_load_dwordx4 v[128:131], v207, s[48:49]
	global_load_dwordx4 v[164:167], v209, s[14:15]
	global_load_dwordx4 v[168:171], v209, s[16:17]
	global_load_dwordx4 v[172:175], v209, s[16:17] offset:16
	global_load_dwordx4 v[176:179], v209, s[14:15] offset:16
	global_load_dword v236, v210, s[10:11]
	global_load_dwordx2 v[220:221], v211, s[6:7]
	global_load_dwordx2 v[222:223], v211, s[6:7] offset:32
	global_load_dwordx2 v[224:225], v211, s[6:7] offset:64
	global_load_dwordx2 v[226:227], v211, s[6:7] offset:96
	global_load_dwordx2 v[228:229], v211, s[6:7] offset:128
	global_load_dwordx2 v[230:231], v211, s[6:7] offset:160
	global_load_dwordx2 v[232:233], v211, s[6:7] offset:192
	global_load_dwordx2 v[234:235], v211, s[6:7] offset:224
.Lcma_nopf:
	s_waitcnt lgkmcnt(0)
	s_barrier
	ds_read_b64 v[88:89], v214
	ds_read_b64 v[90:91], v214 offset:256
	ds_read_b64 v[92:93], v214 offset:512
	ds_read_b64 v[94:95], v214 offset:768
	s_waitcnt lgkmcnt(3)
	v_lshlrev_b32_e32 v56, 16, v0
	v_and_b32_e32 v57, 0xffff0000, v0
	v_lshlrev_b32_e32 v58, 16, v1
	v_and_b32_e32 v59, 0xffff0000, v1
	v_lshlrev_b32_e32 v60, 16, v2
	v_and_b32_e32 v61, 0xffff0000, v2
	v_lshlrev_b32_e32 v62, 16, v3
	v_and_b32_e32 v63, 0xffff0000, v3
	v_sub_f32_e32 v56, v56, v88
	v_sub_f32_e32 v57, v57, v88
	v_sub_f32_e32 v58, v58, v88
	v_sub_f32_e32 v59, v59, v88
	v_sub_f32_e32 v60, v60, v88
	v_sub_f32_e32 v61, v61, v88
	v_sub_f32_e32 v62, v62, v88
	v_sub_f32_e32 v63, v63, v88
	v_mul_f32_e32 v56, v89, v56
	v_mul_f32_e32 v57, v89, v57
	v_mul_f32_e32 v58, v89, v58
	v_mul_f32_e32 v59, v89, v59
	v_mul_f32_e32 v60, v89, v60
	v_mul_f32_e32 v61, v89, v61
	v_mul_f32_e32 v62, v89, v62
	v_mul_f32_e32 v63, v89, v63
	v_fma_f32 v56, v42, v56, v38
	v_fma_f32 v57, v43, v57, v39
	v_fma_f32 v58, v44, v58, v40
	v_fma_f32 v59, v45, v59, v41
	v_fma_f32 v60, v46, v60, v50
	v_fma_f32 v61, v47, v61, v51
	v_fma_f32 v62, v48, v62, v52
	v_fma_f32 v63, v49, v63, v53
	v_cvt_pk_bf16_f32 v64, v56, v57
	v_cvt_pk_bf16_f32 v65, v58, v59
	v_cvt_pk_bf16_f32 v66, v60, v61
	v_cvt_pk_bf16_f32 v67, v62, v63
	ds_write_b128 v212, v[64:67]
	ds_write_b128 v213, v[16:19]
	s_waitcnt lgkmcnt(4)
	v_lshlrev_b32_e32 v56, 16, v4
	v_and_b32_e32 v57, 0xffff0000, v4
	v_lshlrev_b32_e32 v58, 16, v5
	v_and_b32_e32 v59, 0xffff0000, v5
	v_lshlrev_b32_e32 v60, 16, v6
	v_and_b32_e32 v61, 0xffff0000, v6
	v_lshlrev_b32_e32 v62, 16, v7
	v_and_b32_e32 v63, 0xffff0000, v7
	v_sub_f32_e32 v56, v56, v90
	v_sub_f32_e32 v57, v57, v90
	v_sub_f32_e32 v58, v58, v90
	v_sub_f32_e32 v59, v59, v90
	v_sub_f32_e32 v60, v60, v90
	v_sub_f32_e32 v61, v61, v90
	v_sub_f32_e32 v62, v62, v90
	v_sub_f32_e32 v63, v63, v90
	v_mul_f32_e32 v56, v91, v56
	v_mul_f32_e32 v57, v91, v57
	v_mul_f32_e32 v58, v91, v58
	v_mul_f32_e32 v59, v91, v59
	v_mul_f32_e32 v60, v91, v60
	v_mul_f32_e32 v61, v91, v61
	v_mul_f32_e32 v62, v91, v62
	v_mul_f32_e32 v63, v91, v63
	v_fma_f32 v56, v42, v56, v38
	v_fma_f32 v57, v43, v57, v39
	v_fma_f32 v58, v44, v58, v40
	v_fma_f32 v59, v45, v59, v41
	v_fma_f32 v60, v46, v60, v50
	v_fma_f32 v61, v47, v61, v51
	v_fma_f32 v62, v48, v62, v52
	v_fma_f32 v63, v49, v63, v53
	v_cvt_pk_bf16_f32 v64, v56, v57
	v_cvt_pk_bf16_f32 v65, v58, v59
	v_cvt_pk_bf16_f32 v66, v60, v61
	v_cvt_pk_bf16_f32 v67, v62, v63
	ds_write_b128 v212, v[64:67] offset:9216
	ds_write_b128 v213, v[20:23] offset:8704
	s_waitcnt lgkmcnt(5)
	v_lshlrev_b32_e32 v56, 16, v8
	v_and_b32_e32 v57, 0xffff0000, v8
	v_lshlrev_b32_e32 v58, 16, v9
	v_and_b32_e32 v59, 0xffff0000, v9
	v_lshlrev_b32_e32 v60, 16, v10
	v_and_b32_e32 v61, 0xffff0000, v10
	v_lshlrev_b32_e32 v62, 16, v11
	v_and_b32_e32 v63, 0xffff0000, v11
	v_sub_f32_e32 v56, v56, v92
	v_sub_f32_e32 v57, v57, v92
	v_sub_f32_e32 v58, v58, v92
	v_sub_f32_e32 v59, v59, v92
	v_sub_f32_e32 v60, v60, v92
	v_sub_f32_e32 v61, v61, v92
	v_sub_f32_e32 v62, v62, v92
	v_sub_f32_e32 v63, v63, v92
	v_mul_f32_e32 v56, v93, v56
	v_mul_f32_e32 v57, v93, v57
	v_mul_f32_e32 v58, v93, v58
	v_mul_f32_e32 v59, v93, v59
	v_mul_f32_e32 v60, v93, v60
	v_mul_f32_e32 v61, v93, v61
	v_mul_f32_e32 v62, v93, v62
	v_mul_f32_e32 v63, v93, v63
	v_fma_f32 v56, v42, v56, v38
	v_fma_f32 v57, v43, v57, v39
	v_fma_f32 v58, v44, v58, v40
	v_fma_f32 v59, v45, v59, v41
	v_fma_f32 v60, v46, v60, v50
	v_fma_f32 v61, v47, v61, v51
	v_fma_f32 v62, v48, v62, v52
	v_fma_f32 v63, v49, v63, v53
	v_cvt_pk_bf16_f32 v64, v56, v57
	v_cvt_pk_bf16_f32 v65, v58, v59
	v_cvt_pk_bf16_f32 v66, v60, v61
	v_cvt_pk_bf16_f32 v67, v62, v63
	ds_write_b128 v212, v[64:67] offset:18432
	ds_write_b128 v213, v[24:27] offset:17408
	s_waitcnt lgkmcnt(6)
	v_lshlrev_b32_e32 v56, 16, v12
	v_and_b32_e32 v57, 0xffff0000, v12
	v_lshlrev_b32_e32 v58, 16, v13
	v_and_b32_e32 v59, 0xffff0000, v13
	v_lshlrev_b32_e32 v60, 16, v14
	v_and_b32_e32 v61, 0xffff0000, v14
	v_lshlrev_b32_e32 v62, 16, v15
	v_and_b32_e32 v63, 0xffff0000, v15
	v_sub_f32_e32 v56, v56, v94
	v_sub_f32_e32 v57, v57, v94
	v_sub_f32_e32 v58, v58, v94
	v_sub_f32_e32 v59, v59, v94
	v_sub_f32_e32 v60, v60, v94
	v_sub_f32_e32 v61, v61, v94
	v_sub_f32_e32 v62, v62, v94
	v_sub_f32_e32 v63, v63, v94
	v_mul_f32_e32 v56, v95, v56
	v_mul_f32_e32 v57, v95, v57
	v_mul_f32_e32 v58, v95, v58
	v_mul_f32_e32 v59, v95, v59
	v_mul_f32_e32 v60, v95, v60
	v_mul_f32_e32 v61, v95, v61
	v_mul_f32_e32 v62, v95, v62
	v_mul_f32_e32 v63, v95, v63
	v_fma_f32 v56, v42, v56, v38
	v_fma_f32 v57, v43, v57, v39
	v_fma_f32 v58, v44, v58, v40
	v_fma_f32 v59, v45, v59, v41
	v_fma_f32 v60, v46, v60, v50
	v_fma_f32 v61, v47, v61, v51
	v_fma_f32 v62, v48, v62, v52
	v_fma_f32 v63, v49, v63, v53
	v_cvt_pk_bf16_f32 v64, v56, v57
	v_cvt_pk_bf16_f32 v65, v58, v59
	v_cvt_pk_bf16_f32 v66, v60, v61
	v_cvt_pk_bf16_f32 v67, v62, v63
	ds_write_b128 v212, v[64:67] offset:27648
	ds_write_b128 v213, v[28:31] offset:26112
	s_waitcnt lgkmcnt(0)
	s_barrier
	ds_read2_b64 v[12:15], v217 offset1:4
	ds_read2_b64 v[8:11], v217 offset0:8 offset1:12
	ds_read2_b64 v[0:3], v217 offset0:16 offset1:20
	ds_read2_b64 v[4:7], v217 offset0:24 offset1:28
	ds_read_b64_tr_b16 v[18:19], v216
	ds_read_b64_tr_b16 v[20:21], v216 offset:4608
	ds_read_b64_tr_b16 v[22:23], v216 offset:9216
	ds_read_b64_tr_b16 v[24:25], v216 offset:13824
	ds_read_b64_tr_b16 v[26:27], v216 offset:18432
	ds_read_b64_tr_b16 v[28:29], v216 offset:23040
	ds_read_b64_tr_b16 v[30:31], v216 offset:27648
	ds_read_b64_tr_b16 v[32:33], v216 offset:32256
	s_waitcnt lgkmcnt(0)
	ds_read_b64_tr_b16 v[54:55], v216 offset:32
	ds_read_b64_tr_b16 v[56:57], v216 offset:4640
	ds_read_b64_tr_b16 v[58:59], v216 offset:9248
	ds_read_b64_tr_b16 v[60:61], v216 offset:13856
	ds_read_b64_tr_b16 v[62:63], v216 offset:18464
	ds_read_b64_tr_b16 v[64:65], v216 offset:23072
	ds_read_b64_tr_b16 v[66:67], v216 offset:27680
	ds_read_b64_tr_b16 v[68:69], v216 offset:32288
	v_mfma_f32_16x16x32_bf16 v[34:37], v[18:21], v[12:15], 0
	v_mfma_f32_16x16x32_bf16 v[34:37], v[22:25], v[8:11], v[34:37]
	v_mfma_f32_16x16x32_bf16 v[34:37], v[26:29], v[0:3], v[34:37]
	v_mfma_f32_16x16x32_bf16 v[34:37], v[30:33], v[4:7], v[34:37]
	s_waitcnt lgkmcnt(0)
	ds_read_b64_tr_b16 v[18:19], v216 offset:64
	ds_read_b64_tr_b16 v[20:21], v216 offset:4672
	ds_read_b64_tr_b16 v[22:23], v216 offset:9280
	ds_read_b64_tr_b16 v[24:25], v216 offset:13888
	ds_read_b64_tr_b16 v[26:27], v216 offset:18496
	ds_read_b64_tr_b16 v[28:29], v216 offset:23104
	ds_read_b64_tr_b16 v[30:31], v216 offset:27712
	ds_read_b64_tr_b16 v[32:33], v216 offset:32320
	v_mfma_f32_16x16x32_bf16 v[88:91], v[54:57], v[12:15], 0
	v_lshlrev_b32_e32 v38, 16, v70
	v_and_b32_e32 v39, 0xffff0000, v70
	v_lshlrev_b32_e32 v40, 16, v71
	v_and_b32_e32 v41, 0xffff0000, v71
	v_mfma_f32_16x16x32_bf16 v[88:91], v[58:61], v[8:11], v[88:91]
	v_add_f32_e32 v42, v86, v34
	v_add_f32_e32 v43, v86, v35
	v_add_f32_e32 v44, v86, v36
	v_add_f32_e32 v45, v86, v37
	v_mfma_f32_16x16x32_bf16 v[88:91], v[62:65], v[0:3], v[88:91]
	v_mul_f32_e32 v42, v42, v38
	v_mul_f32_e32 v43, v43, v39
	v_mul_f32_e32 v44, v44, v40
	v_mul_f32_e32 v45, v45, v41
	v_mfma_f32_16x16x32_bf16 v[88:91], v[66:69], v[4:7], v[88:91]
	v_cvt_pk_bf16_f32 v46, v42, v43
	v_cvt_pk_bf16_f32 v47, v44, v45
	global_store_dwordx2 v211, v[46:47], s[12:13]
	s_waitcnt lgkmcnt(0)
	ds_read_b64_tr_b16 v[54:55], v216 offset:96
	ds_read_b64_tr_b16 v[56:57], v216 offset:4704
	ds_read_b64_tr_b16 v[58:59], v216 offset:9312
	ds_read_b64_tr_b16 v[60:61], v216 offset:13920
	ds_read_b64_tr_b16 v[62:63], v216 offset:18528
	ds_read_b64_tr_b16 v[64:65], v216 offset:23136
	ds_read_b64_tr_b16 v[66:67], v216 offset:27744
	ds_read_b64_tr_b16 v[68:69], v216 offset:32352
	v_mfma_f32_16x16x32_bf16 v[34:37], v[18:21], v[12:15], 0
	v_lshlrev_b32_e32 v38, 16, v72
	v_and_b32_e32 v39, 0xffff0000, v72
	v_lshlrev_b32_e32 v40, 16, v73
	v_and_b32_e32 v41, 0xffff0000, v73
	v_mfma_f32_16x16x32_bf16 v[34:37], v[22:25], v[8:11], v[34:37]
	v_add_f32_e32 v42, v86, v88
	v_add_f32_e32 v43, v86, v89
	v_add_f32_e32 v44, v86, v90
	v_add_f32_e32 v45, v86, v91
	v_mfma_f32_16x16x32_bf16 v[34:37], v[26:29], v[0:3], v[34:37]
	v_mul_f32_e32 v42, v42, v38
	v_mul_f32_e32 v43, v43, v39
	v_mul_f32_e32 v44, v44, v40
	v_mul_f32_e32 v45, v45, v41
	v_mfma_f32_16x16x32_bf16 v[34:37], v[30:33], v[4:7], v[34:37]
	v_cvt_pk_bf16_f32 v48, v42, v43
	v_cvt_pk_bf16_f32 v49, v44, v45
	global_store_dwordx2 v211, v[48:49], s[12:13] offset:32
	s_waitcnt lgkmcnt(0)
	ds_read_b64_tr_b16 v[18:19], v216 offset:128
	ds_read_b64_tr_b16 v[20:21], v216 offset:4736
	ds_read_b64_tr_b16 v[22:23], v216 offset:9344
	ds_read_b64_tr_b16 v[24:25], v216 offset:13952
	ds_read_b64_tr_b16 v[26:27], v216 offset:18560
	ds_read_b64_tr_b16 v[28:29], v216 offset:23168
	ds_read_b64_tr_b16 v[30:31], v216 offset:27776
	ds_read_b64_tr_b16 v[32:33], v216 offset:32384
	v_mfma_f32_16x16x32_bf16 v[88:91], v[54:57], v[12:15], 0
	v_lshlrev_b32_e32 v38, 16, v74
	v_and_b32_e32 v39, 0xffff0000, v74
	v_lshlrev_b32_e32 v40, 16, v75
	v_and_b32_e32 v41, 0xffff0000, v75
	v_mfma_f32_16x16x32_bf16 v[88:91], v[58:61], v[8:11], v[88:91]
	v_add_f32_e32 v42, v86, v34
	v_add_f32_e32 v43, v86, v35
	v_add_f32_e32 v44, v86, v36
	v_add_f32_e32 v45, v86, v37
	v_mfma_f32_16x16x32_bf16 v[88:91], v[62:65], v[0:3], v[88:91]
	v_mul_f32_e32 v42, v42, v38
	v_mul_f32_e32 v43, v43, v39
	v_mul_f32_e32 v44, v44, v40
	v_mul_f32_e32 v45, v45, v41
	v_mfma_f32_16x16x32_bf16 v[88:91], v[66:69], v[4:7], v[88:91]
	v_cvt_pk_bf16_f32 v46, v42, v43
	v_cvt_pk_bf16_f32 v47, v44, v45
	global_store_dwordx2 v211, v[46:47], s[12:13] offset:64
	s_waitcnt lgkmcnt(0)
	ds_read_b64_tr_b16 v[54:55], v216 offset:160
	ds_read_b64_tr_b16 v[56:57], v216 offset:4768
	ds_read_b64_tr_b16 v[58:59], v216 offset:9376
	ds_read_b64_tr_b16 v[60:61], v216 offset:13984
	ds_read_b64_tr_b16 v[62:63], v216 offset:18592
	ds_read_b64_tr_b16 v[64:65], v216 offset:23200
	ds_read_b64_tr_b16 v[66:67], v216 offset:27808
	ds_read_b64_tr_b16 v[68:69], v216 offset:32416
	v_mfma_f32_16x16x32_bf16 v[34:37], v[18:21], v[12:15], 0
	v_lshlrev_b32_e32 v38, 16, v76
	v_and_b32_e32 v39, 0xffff0000, v76
	v_lshlrev_b32_e32 v40, 16, v77
	v_and_b32_e32 v41, 0xffff0000, v77
	v_mfma_f32_16x16x32_bf16 v[34:37], v[22:25], v[8:11], v[34:37]
	v_add_f32_e32 v42, v86, v88
	v_add_f32_e32 v43, v86, v89
	v_add_f32_e32 v44, v86, v90
	v_add_f32_e32 v45, v86, v91
	v_mfma_f32_16x16x32_bf16 v[34:37], v[26:29], v[0:3], v[34:37]
	v_mul_f32_e32 v42, v42, v38
	v_mul_f32_e32 v43, v43, v39
	v_mul_f32_e32 v44, v44, v40
	v_mul_f32_e32 v45, v45, v41
	v_mfma_f32_16x16x32_bf16 v[34:37], v[30:33], v[4:7], v[34:37]
	v_cvt_pk_bf16_f32 v48, v42, v43
	v_cvt_pk_bf16_f32 v49, v44, v45
	global_store_dwordx2 v211, v[48:49], s[12:13] offset:96
	s_waitcnt lgkmcnt(0)
	ds_read_b64_tr_b16 v[18:19], v216 offset:192
	ds_read_b64_tr_b16 v[20:21], v216 offset:4800
	ds_read_b64_tr_b16 v[22:23], v216 offset:9408
	ds_read_b64_tr_b16 v[24:25], v216 offset:14016
	ds_read_b64_tr_b16 v[26:27], v216 offset:18624
	ds_read_b64_tr_b16 v[28:29], v216 offset:23232
	ds_read_b64_tr_b16 v[30:31], v216 offset:27840
	ds_read_b64_tr_b16 v[32:33], v216 offset:32448
	v_mfma_f32_16x16x32_bf16 v[88:91], v[54:57], v[12:15], 0
	v_lshlrev_b32_e32 v38, 16, v78
	v_and_b32_e32 v39, 0xffff0000, v78
	v_lshlrev_b32_e32 v40, 16, v79
	v_and_b32_e32 v41, 0xffff0000, v79
	v_mfma_f32_16x16x32_bf16 v[88:91], v[58:61], v[8:11], v[88:91]
	v_add_f32_e32 v42, v86, v34
	v_add_f32_e32 v43, v86, v35
	v_add_f32_e32 v44, v86, v36
	v_add_f32_e32 v45, v86, v37
	v_mfma_f32_16x16x32_bf16 v[88:91], v[62:65], v[0:3], v[88:91]
	v_mul_f32_e32 v42, v42, v38
	v_mul_f32_e32 v43, v43, v39
	v_mul_f32_e32 v44, v44, v40
	v_mul_f32_e32 v45, v45, v41
	v_mfma_f32_16x16x32_bf16 v[88:91], v[66:69], v[4:7], v[88:91]
	v_cvt_pk_bf16_f32 v46, v42, v43
	v_cvt_pk_bf16_f32 v47, v44, v45
	global_store_dwordx2 v211, v[46:47], s[12:13] offset:128
	s_waitcnt lgkmcnt(0)
	ds_read_b64_tr_b16 v[54:55], v216 offset:224
	ds_read_b64_tr_b16 v[56:57], v216 offset:4832
	ds_read_b64_tr_b16 v[58:59], v216 offset:9440
	ds_read_b64_tr_b16 v[60:61], v216 offset:14048
	ds_read_b64_tr_b16 v[62:63], v216 offset:18656
	ds_read_b64_tr_b16 v[64:65], v216 offset:23264
	ds_read_b64_tr_b16 v[66:67], v216 offset:27872
	ds_read_b64_tr_b16 v[68:69], v216 offset:32480
	v_mfma_f32_16x16x32_bf16 v[34:37], v[18:21], v[12:15], 0
	v_lshlrev_b32_e32 v38, 16, v80
	v_and_b32_e32 v39, 0xffff0000, v80
	v_lshlrev_b32_e32 v40, 16, v81
	v_and_b32_e32 v41, 0xffff0000, v81
	v_mfma_f32_16x16x32_bf16 v[34:37], v[22:25], v[8:11], v[34:37]
	v_add_f32_e32 v42, v86, v88
	v_add_f32_e32 v43, v86, v89
	v_add_f32_e32 v44, v86, v90
	v_add_f32_e32 v45, v86, v91
	v_mfma_f32_16x16x32_bf16 v[34:37], v[26:29], v[0:3], v[34:37]
	v_mul_f32_e32 v42, v42, v38
	v_mul_f32_e32 v43, v43, v39
	v_mul_f32_e32 v44, v44, v40
	v_mul_f32_e32 v45, v45, v41
	v_mfma_f32_16x16x32_bf16 v[34:37], v[30:33], v[4:7], v[34:37]
	v_cvt_pk_bf16_f32 v48, v42, v43
	v_cvt_pk_bf16_f32 v49, v44, v45
	global_store_dwordx2 v211, v[48:49], s[12:13] offset:160
	s_waitcnt lgkmcnt(0)
	v_mfma_f32_16x16x32_bf16 v[88:91], v[54:57], v[12:15], 0
	v_lshlrev_b32_e32 v38, 16, v82
	v_and_b32_e32 v39, 0xffff0000, v82
	v_lshlrev_b32_e32 v40, 16, v83
	v_and_b32_e32 v41, 0xffff0000, v83
	v_mfma_f32_16x16x32_bf16 v[88:91], v[58:61], v[8:11], v[88:91]
	v_add_f32_e32 v42, v86, v34
	v_add_f32_e32 v43, v86, v35
	v_add_f32_e32 v44, v86, v36
	v_add_f32_e32 v45, v86, v37
	v_mfma_f32_16x16x32_bf16 v[88:91], v[62:65], v[0:3], v[88:91]
	v_mul_f32_e32 v42, v42, v38
	v_mul_f32_e32 v43, v43, v39
	v_mul_f32_e32 v44, v44, v40
	v_mul_f32_e32 v45, v45, v41
	v_mfma_f32_16x16x32_bf16 v[88:91], v[66:69], v[4:7], v[88:91]
	v_cvt_pk_bf16_f32 v46, v42, v43
	v_cvt_pk_bf16_f32 v47, v44, v45
	global_store_dwordx2 v211, v[46:47], s[12:13] offset:192
	v_lshlrev_b32_e32 v38, 16, v84
	v_and_b32_e32 v39, 0xffff0000, v84
	v_lshlrev_b32_e32 v40, 16, v85
	v_and_b32_e32 v41, 0xffff0000, v85
	s_nop 3
	v_add_f32_e32 v42, v86, v88
	v_add_f32_e32 v43, v86, v89
	v_add_f32_e32 v44, v86, v90
	v_add_f32_e32 v45, v86, v91
	v_mul_f32_e32 v42, v42, v38
	v_mul_f32_e32 v43, v43, v39
	v_mul_f32_e32 v44, v44, v40
	v_mul_f32_e32 v45, v45, v41
	v_cvt_pk_bf16_f32 v48, v42, v43
	v_cvt_pk_bf16_f32 v49, v44, v45
	global_store_dwordx2 v211, v[48:49], s[12:13] offset:224
	s_add_i32 s5, s5, 1
	s_add_i32 s3, s3, -1
	s_cmp_gt_u32 s3, 0
	s_cbranch_scc1 .Lcma_top

.Lcmb_nostat:
	s_branch .Lcmb_copy
.Lcmb_top:
	s_waitcnt vmcnt(8)
